# EpiGU: output address kept in a VGPR pair and stepped by a constant per row block (replaces two 64-bit mads + 6 moves/adds per block)
# speedup vs baseline: 1.0075x; 1.0038x over previous
;     __device__ __forceinline__ void operator()(const f32x4 (&acc)[2][2][4][2], const Unit& u, int wr, int wc, int fr, int fq) const {
;         const int row0 = u.pm * BM + wr * 64 + fr;
; #pragma unroll
;         for (int ai = 0; ai < 2; ++ai)
; #pragma unroll
;             for (int m = 0; m < 4; ++m) {
;                 const int row = row0 + ai * HALF + m * 16;
;                 float rs;
;                 if (rsc) rs = rsc[row - rbase];
;                 else {
;                     const f32x4* pp = (const f32x4*)(part + (size_t)row * 16);
;                     const f32x4 p0 = pp[0], p1 = pp[1], p2 = pp[2], p3 = pp[3];
;                     const float ssq = ((p0[0] + p0[1]) + (p0[2] + p0[3])) + ((p1[0] + p1[1]) + (p1[2] + p1[3])) + ((p2[0] + p2[1]) + (p2[2] + p2[3])) + ((p3[0] + p3[1]) + (p3[2] + p3[3]));
;                     rs = __builtin_amdgcn_rsqf(ssq * (1.0f / 1024.0f) + 1e-6f);
;                 }
.LBB0_743:
	s_mov_b32 s100, 0x16000
	s_mov_b32 s101, 0
	s_mov_b32 s98, 0x6e000
	s_mov_b32 s99, 0
	v_lshl_add_u32 v148, s26, 8, v1
	s_mov_b64 s[26:27], -1
	s_and_b64 vcc, exec, s[36:37]
	v_ashrrev_i32_e32 v149, 31, v148
	s_cbranch_vccz .LBB0_745
	v_lshlrev_b64 v[156:157], 6, v[148:149]
	v_lshl_add_u64 v[168:169], s[8:9], 0, v[156:157]
	global_load_dwordx4 v[156:159], v[168:169], off
	global_load_dwordx4 v[160:163], v[168:169], off offset:16
	global_load_dwordx4 v[164:167], v[168:169], off offset:32
	s_nop 0
	global_load_dwordx4 v[168:171], v[168:169], off offset:48
	s_mov_b64 s[26:27], 0
	s_waitcnt vmcnt(0)
	v_mov_b32_e32 v172, v157
	v_mov_b32_e32 v173, v158
	v_mov_b32_e32 v157, v159
	v_mov_b32_e32 v158, v161
	v_mov_b32_e32 v159, v162
	v_mov_b32_e32 v161, v163
	v_pk_add_f32 v[156:157], v[172:173], v[156:157]
	v_pk_add_f32 v[158:159], v[158:159], v[160:161]
	v_pk_add_f32 v[156:157], v[156:157], v[156:157] op_sel:[0,1] op_sel_hi:[1,0]
	v_pk_add_f32 v[158:159], v[158:159], v[158:159] op_sel:[0,1] op_sel_hi:[1,0]
	v_add_f32_e32 v162, v164, v165
	v_add_f32_e32 v164, v166, v167
	v_mov_b32_e32 v163, v170
	v_mov_b32_e32 v165, v171
	v_mov_b32_e32 v157, v168
	v_mov_b32_e32 v159, v169
	v_pk_add_f32 v[156:157], v[156:157], v[158:159]
	v_pk_add_f32 v[158:159], v[162:163], v[164:165]
	s_nop 0
	v_pk_add_f32 v[156:157], v[156:157], v[158:159]
	s_nop 0
	v_add_f32_e32 v150, v156, v157
	v_fmamk_f32 v150, v150, 0x3a800000, v155
	v_rsq_f32_e32 v150, v150

; __device__ __forceinline__ unsigned cvt_pk_bf16(float lo, float hi) { f32x2 v = {lo, hi}; return __builtin_bit_cast(unsigned, __builtin_convertvector(v, nbf16x2e)); }
;     __device__ __forceinline__ void operator()(const f32x4 (&acc)[2][2][4][2], const Unit& u, int wr, int wc, int fr, int fq) const {
;     ...
;                 const int row = row0 + ai * HALF + m * 16;
;                 float rs;
;                 if (rsc) rs = rsc[row - rbase];
;                 else {
;                     const f32x4* pp = (const f32x4*)(part + (size_t)row * 16);
;                     const f32x4 p0 = pp[0], p1 = pp[1], p2 = pp[2], p3 = pp[3];
;                     const float ssq = ((p0[0] + p0[1]) + (p0[2] + p0[3])) + ((p1[0] + p1[1]) + (p1[2] + p1[3])) + ((p2[0] + p2[1]) + (p2[2] + p2[3])) + ((p3[0] + p3[1]) + (p3[2] + p3[3]));
;                     rs = __builtin_amdgcn_rsqf(ssq * (1.0f / 1024.0f) + 1e-6f);
;                 }
;                 float v[8];
; #pragma unroll
;                 for (int n = 0; n < 2; ++n)
; #pragma unroll
;                     for (int i = 0; i < 4; ++i) { const float g = acc[ai][0][m][n][i] * rs, up = acc[ai][1][m][n][i] * rs; v[4 * n + i] = g * __builtin_amdgcn_rcpf(1.0f + __expf(-g)) * up; }
;                 u32x4 w; w.x = cvt_pk_bf16(v[0], v[1]); w.y = cvt_pk_bf16(v[2], v[3]); w.z = cvt_pk_bf16(v[4], v[5]); w.w = cvt_pk_bf16(v[6], v[7]);
;                 *(u32x4*)(O + (size_t)row * 2816 + u.pn * HALF + wc * 32 + 8 * fq) = w;
.LBB0_747:
	s_waitcnt lgkmcnt(0)
	v_pk_mul_f32 v[126:127], v[126:127], v[150:151] op_sel_hi:[1,0]
	v_pk_mul_f32 v[128:129], v[128:129], v[150:151] op_sel_hi:[1,0]
	v_mul_f32_e32 v157, 0xbfb8aa3b, v126
	v_exp_f32_e32 v157, v157
	v_mul_f32_e32 v158, 0xbfb8aa3b, v127
	v_exp_f32_e32 v159, v158
	v_pk_mul_f32 v[118:119], v[118:119], v[150:151] op_sel_hi:[1,0]
	v_add_f32_e32 v157, 1.0, v157
	v_rcp_f32_e32 v158, v157
	v_add_f32_e32 v157, 1.0, v159
	v_mul_f32_e32 v159, 0xbfb8aa3b, v128
	v_exp_f32_e32 v160, v159
	v_mul_f32_e32 v159, 0xbfb8aa3b, v129
	v_exp_f32_e32 v161, v159
	v_rcp_f32_e32 v159, v157
	v_add_f32_e32 v157, 1.0, v160
	v_rcp_f32_e32 v160, v157
	v_add_f32_e32 v157, 1.0, v161
	v_rcp_f32_e32 v161, v157
	v_pk_mul_f32 v[126:127], v[126:127], v[158:159]
	v_pk_mul_f32 v[122:123], v[122:123], v[150:151] op_sel_hi:[1,0]
	v_pk_mul_f32 v[118:119], v[118:119], v[126:127]
	v_pk_mul_f32 v[126:127], v[128:129], v[160:161]
	v_mul_f32_e32 v128, 0xbfb8aa3b, v122
	v_exp_f32_e32 v128, v128
	v_pk_mul_f32 v[120:121], v[120:121], v[150:151] op_sel_hi:[1,0]
	v_pk_mul_f32 v[124:125], v[124:125], v[150:151] op_sel_hi:[1,0]
	v_pk_mul_f32 v[120:121], v[120:121], v[126:127]
	v_mul_f32_e32 v126, 0xbfb8aa3b, v123
	v_exp_f32_e32 v127, v126
	v_add_f32_e32 v126, 1.0, v128
	v_mul_f32_e32 v128, 0xbfb8aa3b, v124
	v_mul_f32_e32 v129, 0xbfb8aa3b, v125
	v_exp_f32_e32 v128, v128
	v_exp_f32_e32 v129, v129
	v_add_f32_e32 v127, 1.0, v127
	v_rcp_f32_e32 v126, v126
	v_rcp_f32_e32 v127, v127
	v_add_f32_e32 v128, 1.0, v128
	v_add_f32_e32 v129, 1.0, v129
	v_rcp_f32_e32 v128, v128
	v_rcp_f32_e32 v129, v129
	v_pk_mul_f32 v[114:115], v[114:115], v[150:151] op_sel_hi:[1,0]
	v_pk_mul_f32 v[122:123], v[122:123], v[126:127]
	s_lshl_b32 s24, s24, 7
	v_pk_mul_f32 v[122:123], v[114:115], v[122:123]
	v_pk_mul_f32 v[114:115], v[116:117], v[150:151] op_sel_hi:[1,0]
	v_pk_mul_f32 v[116:117], v[124:125], v[128:129]
	s_ashr_i32 s25, s24, 31
	v_pk_mul_f32 v[124:125], v[114:115], v[116:117]
	v_cvt_pk_bf16_f32 v114, v118, v119
	v_mov_b64_e32 v[118:119], s[34:35]
	v_mad_u64_u32 v[118:119], s[26:27], v148, s68, v[118:119]
	v_cvt_pk_bf16_f32 v115, v120, v121
	v_mov_b32_e32 v120, v119
	v_mad_u64_u32 v[120:121], s[26:27], v149, s68, v[120:121]
	v_mov_b32_e32 v119, v120
	v_lshl_add_u64 v[118:119], s[24:25], 1, v[118:119]
	v_lshl_add_u64 v[118:119], v[118:119], 0, s[4:5]
	v_cvt_pk_bf16_f32 v116, v122, v123
	v_cvt_pk_bf16_f32 v117, v124, v125
	v_lshl_add_u64 v[118:119], v[118:119], 0, v[138:139]
	v_mov_b64_e32 v[236:237], v[118:119]
	global_store_dwordx4 v[118:119], v[114:117], off
	s_mov_b64 s[26:27], -1
	s_and_b64 vcc, exec, s[36:37]
	v_or_b32_e32 v114, 16, v148
	v_ashrrev_i32_e32 v115, 31, v114
	s_cbranch_vccz .LBB0_749
	v_lshlrev_b64 v[116:117], 6, v[114:115]
	v_lshl_add_u64 v[128:129], s[8:9], 0, v[116:117]
	global_load_dwordx4 v[116:119], v[128:129], off
	global_load_dwordx4 v[120:123], v[128:129], off offset:16
	global_load_dwordx4 v[124:127], v[128:129], off offset:32
	global_load_dwordx4 v[158:161], v[128:129], off offset:48
	s_mov_b64 s[26:27], 0
	s_waitcnt vmcnt(0)
	v_mov_b32_e32 v128, v117
	v_mov_b32_e32 v129, v118
	v_mov_b32_e32 v117, v119
	v_mov_b32_e32 v118, v121
	v_mov_b32_e32 v119, v122
	v_mov_b32_e32 v121, v123
	v_pk_add_f32 v[116:117], v[128:129], v[116:117]
	v_pk_add_f32 v[118:119], v[118:119], v[120:121]
	v_pk_add_f32 v[116:117], v[116:117], v[116:117] op_sel:[0,1] op_sel_hi:[1,0]
	v_pk_add_f32 v[118:119], v[118:119], v[118:119] op_sel:[0,1] op_sel_hi:[1,0]
	v_add_f32_e32 v122, v124, v125
	v_add_f32_e32 v124, v126, v127
	v_mov_b32_e32 v123, v160
	v_mov_b32_e32 v125, v161
	v_mov_b32_e32 v117, v158
	v_mov_b32_e32 v119, v159
	v_pk_add_f32 v[116:117], v[116:117], v[118:119]
	v_pk_add_f32 v[118:119], v[122:123], v[124:125]
	s_nop 0
	v_pk_add_f32 v[116:117], v[116:117], v[118:119]
	s_nop 0
	v_add_f32_e32 v116, v116, v117
	v_fmamk_f32 v116, v116, 0x3a800000, v155
	v_rsq_f32_e32 v116, v116

; __device__ __forceinline__ unsigned cvt_pk_bf16(float lo, float hi) { f32x2 v = {lo, hi}; return __builtin_bit_cast(unsigned, __builtin_convertvector(v, nbf16x2e)); }
;     __device__ __forceinline__ void operator()(const f32x4 (&acc)[2][2][4][2], const Unit& u, int wr, int wc, int fr, int fq) const {
;     ...
;                 const int row = row0 + ai * HALF + m * 16;
;                 float rs;
;                 if (rsc) rs = rsc[row - rbase];
;                 else {
;                     const f32x4* pp = (const f32x4*)(part + (size_t)row * 16);
;                     const f32x4 p0 = pp[0], p1 = pp[1], p2 = pp[2], p3 = pp[3];
;                     const float ssq = ((p0[0] + p0[1]) + (p0[2] + p0[3])) + ((p1[0] + p1[1]) + (p1[2] + p1[3])) + ((p2[0] + p2[1]) + (p2[2] + p2[3])) + ((p3[0] + p3[1]) + (p3[2] + p3[3]));
;                     rs = __builtin_amdgcn_rsqf(ssq * (1.0f / 1024.0f) + 1e-6f);
;                 }
;                 float v[8];
; #pragma unroll
;                 for (int n = 0; n < 2; ++n)
; #pragma unroll
;                     for (int i = 0; i < 4; ++i) { const float g = acc[ai][0][m][n][i] * rs, up = acc[ai][1][m][n][i] * rs; v[4 * n + i] = g * __builtin_amdgcn_rcpf(1.0f + __expf(-g)) * up; }
;                 u32x4 w; w.x = cvt_pk_bf16(v[0], v[1]); w.y = cvt_pk_bf16(v[2], v[3]); w.z = cvt_pk_bf16(v[4], v[5]); w.w = cvt_pk_bf16(v[6], v[7]);
;                 *(u32x4*)(O + (size_t)row * 2816 + u.pn * HALF + wc * 32 + 8 * fq) = w;
.LBB0_751:
	s_waitcnt lgkmcnt(0)
	v_pk_mul_f32 v[110:111], v[110:111], v[116:117] op_sel_hi:[1,0]
	s_and_b64 vcc, exec, s[36:37]
	v_mul_f32_e32 v117, 0xbfb8aa3b, v110
	v_exp_f32_e32 v117, v117
	v_mul_f32_e32 v118, 0xbfb8aa3b, v111
	v_exp_f32_e32 v119, v118
	v_pk_mul_f32 v[102:103], v[102:103], v[116:117] op_sel_hi:[1,0]
	v_add_f32_e32 v117, 1.0, v117
	v_rcp_f32_e32 v118, v117
	v_add_f32_e32 v117, 1.0, v119
	v_pk_mul_f32 v[112:113], v[112:113], v[116:117] op_sel_hi:[1,0]
	s_nop 0
	v_mul_f32_e32 v119, 0xbfb8aa3b, v112
	v_exp_f32_e32 v120, v119
	v_mul_f32_e32 v119, 0xbfb8aa3b, v113
	v_exp_f32_e32 v121, v119
	v_rcp_f32_e32 v119, v117
	v_add_f32_e32 v117, 1.0, v120
	v_rcp_f32_e32 v120, v117
	v_add_f32_e32 v117, 1.0, v121
	v_rcp_f32_e32 v121, v117
	v_pk_mul_f32 v[110:111], v[110:111], v[118:119]
	v_pk_mul_f32 v[106:107], v[106:107], v[116:117] op_sel_hi:[1,0]
	v_pk_mul_f32 v[102:103], v[102:103], v[110:111]
	v_pk_mul_f32 v[110:111], v[112:113], v[120:121]
	v_mul_f32_e32 v112, 0xbfb8aa3b, v106
	v_exp_f32_e32 v112, v112
	v_pk_mul_f32 v[104:105], v[104:105], v[116:117] op_sel_hi:[1,0]
	v_pk_mul_f32 v[108:109], v[108:109], v[116:117] op_sel_hi:[1,0]
	v_pk_mul_f32 v[104:105], v[104:105], v[110:111]
	v_mul_f32_e32 v110, 0xbfb8aa3b, v107
	v_exp_f32_e32 v111, v110
	v_add_f32_e32 v110, 1.0, v112
	v_mul_f32_e32 v112, 0xbfb8aa3b, v108
	v_mul_f32_e32 v113, 0xbfb8aa3b, v109
	v_exp_f32_e32 v112, v112
	v_exp_f32_e32 v113, v113
	v_add_f32_e32 v111, 1.0, v111
	v_rcp_f32_e32 v110, v110
	v_rcp_f32_e32 v111, v111
	v_add_f32_e32 v112, 1.0, v112
	v_add_f32_e32 v113, 1.0, v113
	v_rcp_f32_e32 v112, v112
	v_rcp_f32_e32 v113, v113
	v_pk_mul_f32 v[98:99], v[98:99], v[116:117] op_sel_hi:[1,0]
	v_pk_mul_f32 v[106:107], v[106:107], v[110:111]
	s_nop 0
	v_pk_mul_f32 v[106:107], v[98:99], v[106:107]
	v_pk_mul_f32 v[98:99], v[100:101], v[116:117] op_sel_hi:[1,0]
	v_pk_mul_f32 v[100:101], v[108:109], v[112:113]
	s_nop 0
	v_pk_mul_f32 v[108:109], v[98:99], v[100:101]
	v_cvt_pk_bf16_f32 v98, v102, v103
	v_cvt_pk_bf16_f32 v99, v104, v105
	v_cvt_pk_bf16_f32 v100, v106, v107
	v_cvt_pk_bf16_f32 v101, v108, v109
	v_lshl_add_u64 v[236:237], v[236:237], 0, s[100:101]
	global_store_dwordx4 v[236:237], v[98:101], off
	s_mov_b64 s[26:27], -1
	s_nop 0
	v_or_b32_e32 v98, 32, v148
	v_ashrrev_i32_e32 v99, 31, v98
	s_cbranch_vccz .LBB0_753
	v_lshlrev_b64 v[100:101], 6, v[98:99]
	v_lshl_add_u64 v[112:113], s[8:9], 0, v[100:101]
	global_load_dwordx4 v[100:103], v[112:113], off
	global_load_dwordx4 v[104:107], v[112:113], off offset:16
	global_load_dwordx4 v[108:111], v[112:113], off offset:32
	s_nop 0
	global_load_dwordx4 v[112:115], v[112:113], off offset:48
	s_mov_b64 s[26:27], 0
	s_waitcnt vmcnt(0)
	v_mov_b32_e32 v116, v101
	v_mov_b32_e32 v117, v102
	v_mov_b32_e32 v101, v103
	v_mov_b32_e32 v102, v105
	v_mov_b32_e32 v103, v106
	v_mov_b32_e32 v105, v107
	v_pk_add_f32 v[100:101], v[116:117], v[100:101]
	v_pk_add_f32 v[102:103], v[102:103], v[104:105]
	v_pk_add_f32 v[100:101], v[100:101], v[100:101] op_sel:[0,1] op_sel_hi:[1,0]
	v_pk_add_f32 v[102:103], v[102:103], v[102:103] op_sel:[0,1] op_sel_hi:[1,0]
	v_add_f32_e32 v106, v108, v109
	v_add_f32_e32 v108, v110, v111
	v_mov_b32_e32 v107, v114
	v_mov_b32_e32 v109, v115
	v_mov_b32_e32 v101, v112
	v_mov_b32_e32 v103, v113
	v_pk_add_f32 v[100:101], v[100:101], v[102:103]
	v_pk_add_f32 v[102:103], v[106:107], v[108:109]
	s_nop 0
	v_pk_add_f32 v[100:101], v[100:101], v[102:103]
	s_nop 0
	v_add_f32_e32 v100, v100, v101
	v_fmamk_f32 v100, v100, 0x3a800000, v155
	v_rsq_f32_e32 v100, v100

; __device__ __forceinline__ unsigned cvt_pk_bf16(float lo, float hi) { f32x2 v = {lo, hi}; return __builtin_bit_cast(unsigned, __builtin_convertvector(v, nbf16x2e)); }
;     __device__ __forceinline__ void operator()(const f32x4 (&acc)[2][2][4][2], const Unit& u, int wr, int wc, int fr, int fq) const {
;     ...
;                 const int row = row0 + ai * HALF + m * 16;
;                 float rs;
;                 if (rsc) rs = rsc[row - rbase];
;                 else {
;                     const f32x4* pp = (const f32x4*)(part + (size_t)row * 16);
;                     const f32x4 p0 = pp[0], p1 = pp[1], p2 = pp[2], p3 = pp[3];
;                     const float ssq = ((p0[0] + p0[1]) + (p0[2] + p0[3])) + ((p1[0] + p1[1]) + (p1[2] + p1[3])) + ((p2[0] + p2[1]) + (p2[2] + p2[3])) + ((p3[0] + p3[1]) + (p3[2] + p3[3]));
;                     rs = __builtin_amdgcn_rsqf(ssq * (1.0f / 1024.0f) + 1e-6f);
;                 }
;                 float v[8];
; #pragma unroll
;                 for (int n = 0; n < 2; ++n)
; #pragma unroll
;                     for (int i = 0; i < 4; ++i) { const float g = acc[ai][0][m][n][i] * rs, up = acc[ai][1][m][n][i] * rs; v[4 * n + i] = g * __builtin_amdgcn_rcpf(1.0f + __expf(-g)) * up; }
;                 u32x4 w; w.x = cvt_pk_bf16(v[0], v[1]); w.y = cvt_pk_bf16(v[2], v[3]); w.z = cvt_pk_bf16(v[4], v[5]); w.w = cvt_pk_bf16(v[6], v[7]);
;                 *(u32x4*)(O + (size_t)row * 2816 + u.pn * HALF + wc * 32 + 8 * fq) = w;
.LBB0_755:
	s_waitcnt lgkmcnt(0)
	v_pk_mul_f32 v[94:95], v[94:95], v[100:101] op_sel_hi:[1,0]
	s_and_b64 vcc, exec, s[36:37]
	v_mul_f32_e32 v101, 0xbfb8aa3b, v94
	v_exp_f32_e32 v101, v101
	v_mul_f32_e32 v102, 0xbfb8aa3b, v95
	v_exp_f32_e32 v103, v102
	v_pk_mul_f32 v[86:87], v[86:87], v[100:101] op_sel_hi:[1,0]
	v_add_f32_e32 v101, 1.0, v101
	v_rcp_f32_e32 v102, v101
	v_add_f32_e32 v101, 1.0, v103
	v_pk_mul_f32 v[96:97], v[96:97], v[100:101] op_sel_hi:[1,0]
	s_nop 0
	v_mul_f32_e32 v103, 0xbfb8aa3b, v96
	v_exp_f32_e32 v104, v103
	v_mul_f32_e32 v103, 0xbfb8aa3b, v97
	v_exp_f32_e32 v105, v103
	v_rcp_f32_e32 v103, v101
	v_add_f32_e32 v101, 1.0, v104
	v_rcp_f32_e32 v104, v101
	v_add_f32_e32 v101, 1.0, v105
	v_rcp_f32_e32 v105, v101
	v_pk_mul_f32 v[94:95], v[94:95], v[102:103]
	v_pk_mul_f32 v[90:91], v[90:91], v[100:101] op_sel_hi:[1,0]
	v_pk_mul_f32 v[86:87], v[86:87], v[94:95]
	v_pk_mul_f32 v[94:95], v[96:97], v[104:105]
	v_mul_f32_e32 v96, 0xbfb8aa3b, v90
	v_exp_f32_e32 v96, v96
	v_pk_mul_f32 v[88:89], v[88:89], v[100:101] op_sel_hi:[1,0]
	v_pk_mul_f32 v[92:93], v[92:93], v[100:101] op_sel_hi:[1,0]
	v_pk_mul_f32 v[88:89], v[88:89], v[94:95]
	v_mul_f32_e32 v94, 0xbfb8aa3b, v91
	v_exp_f32_e32 v95, v94
	v_add_f32_e32 v94, 1.0, v96
	v_mul_f32_e32 v96, 0xbfb8aa3b, v92
	v_mul_f32_e32 v97, 0xbfb8aa3b, v93
	v_exp_f32_e32 v96, v96
	v_exp_f32_e32 v97, v97
	v_add_f32_e32 v95, 1.0, v95
	v_rcp_f32_e32 v94, v94
	v_rcp_f32_e32 v95, v95
	v_add_f32_e32 v96, 1.0, v96
	v_add_f32_e32 v97, 1.0, v97
	v_rcp_f32_e32 v96, v96
	v_rcp_f32_e32 v97, v97
	v_pk_mul_f32 v[82:83], v[82:83], v[100:101] op_sel_hi:[1,0]
	v_pk_mul_f32 v[90:91], v[90:91], v[94:95]
	s_nop 0
	v_pk_mul_f32 v[90:91], v[82:83], v[90:91]
	v_pk_mul_f32 v[82:83], v[84:85], v[100:101] op_sel_hi:[1,0]
	v_pk_mul_f32 v[84:85], v[92:93], v[96:97]
	s_nop 0
	v_pk_mul_f32 v[92:93], v[82:83], v[84:85]
	v_cvt_pk_bf16_f32 v82, v86, v87
	v_cvt_pk_bf16_f32 v83, v88, v89
	v_cvt_pk_bf16_f32 v84, v90, v91
	v_cvt_pk_bf16_f32 v85, v92, v93
	v_lshl_add_u64 v[236:237], v[236:237], 0, s[100:101]
	global_store_dwordx4 v[236:237], v[82:85], off
	s_mov_b64 s[26:27], -1
	s_nop 0
	v_or_b32_e32 v82, 48, v148
	v_ashrrev_i32_e32 v83, 31, v82
	s_cbranch_vccz .LBB0_757
	v_lshlrev_b64 v[84:85], 6, v[82:83]
	v_lshl_add_u64 v[96:97], s[8:9], 0, v[84:85]
	global_load_dwordx4 v[84:87], v[96:97], off
	global_load_dwordx4 v[88:91], v[96:97], off offset:16
	global_load_dwordx4 v[92:95], v[96:97], off offset:32
	s_nop 0
	global_load_dwordx4 v[96:99], v[96:97], off offset:48
	s_mov_b64 s[26:27], 0
	s_waitcnt vmcnt(0)
	v_mov_b32_e32 v100, v85
	v_mov_b32_e32 v101, v86
	v_mov_b32_e32 v85, v87
	v_mov_b32_e32 v86, v89
	v_mov_b32_e32 v87, v90
	v_mov_b32_e32 v89, v91
	v_pk_add_f32 v[84:85], v[100:101], v[84:85]
	v_pk_add_f32 v[86:87], v[86:87], v[88:89]
	v_pk_add_f32 v[84:85], v[84:85], v[84:85] op_sel:[0,1] op_sel_hi:[1,0]
	v_pk_add_f32 v[86:87], v[86:87], v[86:87] op_sel:[0,1] op_sel_hi:[1,0]
	v_add_f32_e32 v90, v92, v93
	v_add_f32_e32 v92, v94, v95
	v_mov_b32_e32 v91, v98
	v_mov_b32_e32 v93, v99
	v_mov_b32_e32 v85, v96
	v_mov_b32_e32 v87, v97
	v_pk_add_f32 v[84:85], v[84:85], v[86:87]
	v_pk_add_f32 v[86:87], v[90:91], v[92:93]
	s_nop 0
	v_pk_add_f32 v[84:85], v[84:85], v[86:87]
	s_nop 0
	v_add_f32_e32 v84, v84, v85
	v_fmamk_f32 v84, v84, 0x3a800000, v155
	v_rsq_f32_e32 v84, v84

; __device__ __forceinline__ unsigned cvt_pk_bf16(float lo, float hi) { f32x2 v = {lo, hi}; return __builtin_bit_cast(unsigned, __builtin_convertvector(v, nbf16x2e)); }
;     __device__ __forceinline__ void operator()(const f32x4 (&acc)[2][2][4][2], const Unit& u, int wr, int wc, int fr, int fq) const {
;     ...
;                 const int row = row0 + ai * HALF + m * 16;
;                 float rs;
;                 if (rsc) rs = rsc[row - rbase];
;                 else {
;                     const f32x4* pp = (const f32x4*)(part + (size_t)row * 16);
;                     const f32x4 p0 = pp[0], p1 = pp[1], p2 = pp[2], p3 = pp[3];
;                     const float ssq = ((p0[0] + p0[1]) + (p0[2] + p0[3])) + ((p1[0] + p1[1]) + (p1[2] + p1[3])) + ((p2[0] + p2[1]) + (p2[2] + p2[3])) + ((p3[0] + p3[1]) + (p3[2] + p3[3]));
;                     rs = __builtin_amdgcn_rsqf(ssq * (1.0f / 1024.0f) + 1e-6f);
;                 }
;                 float v[8];
; #pragma unroll
;                 for (int n = 0; n < 2; ++n)
; #pragma unroll
;                     for (int i = 0; i < 4; ++i) { const float g = acc[ai][0][m][n][i] * rs, up = acc[ai][1][m][n][i] * rs; v[4 * n + i] = g * __builtin_amdgcn_rcpf(1.0f + __expf(-g)) * up; }
;                 u32x4 w; w.x = cvt_pk_bf16(v[0], v[1]); w.y = cvt_pk_bf16(v[2], v[3]); w.z = cvt_pk_bf16(v[4], v[5]); w.w = cvt_pk_bf16(v[6], v[7]);
;                 *(u32x4*)(O + (size_t)row * 2816 + u.pn * HALF + wc * 32 + 8 * fq) = w;
.LBB0_759:
	s_waitcnt lgkmcnt(0)
	v_pk_mul_f32 v[78:79], v[78:79], v[84:85] op_sel_hi:[1,0]
	s_and_b64 vcc, exec, s[36:37]
	v_mul_f32_e32 v85, 0xbfb8aa3b, v78
	v_exp_f32_e32 v85, v85
	v_mul_f32_e32 v86, 0xbfb8aa3b, v79
	v_exp_f32_e32 v87, v86
	v_pk_mul_f32 v[70:71], v[70:71], v[84:85] op_sel_hi:[1,0]
	v_add_f32_e32 v85, 1.0, v85
	v_rcp_f32_e32 v86, v85
	v_add_f32_e32 v85, 1.0, v87
	v_pk_mul_f32 v[80:81], v[80:81], v[84:85] op_sel_hi:[1,0]
	s_nop 0
	v_mul_f32_e32 v87, 0xbfb8aa3b, v80
	v_exp_f32_e32 v88, v87
	v_mul_f32_e32 v87, 0xbfb8aa3b, v81
	v_exp_f32_e32 v89, v87
	v_rcp_f32_e32 v87, v85
	v_add_f32_e32 v85, 1.0, v88
	v_rcp_f32_e32 v88, v85
	v_add_f32_e32 v85, 1.0, v89
	v_rcp_f32_e32 v89, v85
	v_pk_mul_f32 v[78:79], v[78:79], v[86:87]
	v_pk_mul_f32 v[74:75], v[74:75], v[84:85] op_sel_hi:[1,0]
	v_pk_mul_f32 v[70:71], v[70:71], v[78:79]
	v_pk_mul_f32 v[78:79], v[80:81], v[88:89]
	v_mul_f32_e32 v80, 0xbfb8aa3b, v74
	v_exp_f32_e32 v80, v80
	v_pk_mul_f32 v[72:73], v[72:73], v[84:85] op_sel_hi:[1,0]
	v_pk_mul_f32 v[76:77], v[76:77], v[84:85] op_sel_hi:[1,0]
	v_pk_mul_f32 v[72:73], v[72:73], v[78:79]
	v_mul_f32_e32 v78, 0xbfb8aa3b, v75
	v_exp_f32_e32 v79, v78
	v_add_f32_e32 v78, 1.0, v80
	v_mul_f32_e32 v80, 0xbfb8aa3b, v76
	v_mul_f32_e32 v81, 0xbfb8aa3b, v77
	v_exp_f32_e32 v80, v80
	v_exp_f32_e32 v81, v81
	v_add_f32_e32 v79, 1.0, v79
	v_rcp_f32_e32 v78, v78
	v_rcp_f32_e32 v79, v79
	v_add_f32_e32 v80, 1.0, v80
	v_add_f32_e32 v81, 1.0, v81
	v_rcp_f32_e32 v80, v80
	v_rcp_f32_e32 v81, v81
	v_pk_mul_f32 v[66:67], v[66:67], v[84:85] op_sel_hi:[1,0]
	v_pk_mul_f32 v[74:75], v[74:75], v[78:79]
	s_nop 0
	v_pk_mul_f32 v[74:75], v[66:67], v[74:75]
	v_pk_mul_f32 v[66:67], v[68:69], v[84:85] op_sel_hi:[1,0]
	v_pk_mul_f32 v[68:69], v[76:77], v[80:81]
	s_nop 0
	v_pk_mul_f32 v[76:77], v[66:67], v[68:69]
	v_cvt_pk_bf16_f32 v66, v70, v71
	v_cvt_pk_bf16_f32 v67, v72, v73
	v_cvt_pk_bf16_f32 v68, v74, v75
	v_cvt_pk_bf16_f32 v69, v76, v77
	v_lshl_add_u64 v[236:237], v[236:237], 0, s[100:101]
	global_store_dwordx4 v[236:237], v[66:69], off
	s_mov_b64 s[26:27], -1
	s_nop 0
	v_add_u32_e32 v66, 0x80, v148
	v_ashrrev_i32_e32 v67, 31, v66
	s_cbranch_vccz .LBB0_761
	v_lshlrev_b64 v[68:69], 6, v[66:67]
	v_lshl_add_u64 v[80:81], s[8:9], 0, v[68:69]
	global_load_dwordx4 v[68:71], v[80:81], off
	global_load_dwordx4 v[72:75], v[80:81], off offset:16
	global_load_dwordx4 v[76:79], v[80:81], off offset:32
	s_nop 0
	global_load_dwordx4 v[80:83], v[80:81], off offset:48
	s_mov_b64 s[26:27], 0
	s_waitcnt vmcnt(0)
	v_mov_b32_e32 v84, v69
	v_mov_b32_e32 v85, v70
	v_mov_b32_e32 v69, v71
	v_mov_b32_e32 v70, v73
	v_mov_b32_e32 v71, v74
	v_mov_b32_e32 v73, v75
	v_pk_add_f32 v[68:69], v[84:85], v[68:69]
	v_pk_add_f32 v[70:71], v[70:71], v[72:73]
	v_pk_add_f32 v[68:69], v[68:69], v[68:69] op_sel:[0,1] op_sel_hi:[1,0]
	v_pk_add_f32 v[70:71], v[70:71], v[70:71] op_sel:[0,1] op_sel_hi:[1,0]
	v_add_f32_e32 v74, v76, v77
	v_add_f32_e32 v76, v78, v79
	v_mov_b32_e32 v75, v82
	v_mov_b32_e32 v77, v83
	v_mov_b32_e32 v69, v80
	v_mov_b32_e32 v71, v81
	v_pk_add_f32 v[68:69], v[68:69], v[70:71]
	v_pk_add_f32 v[70:71], v[74:75], v[76:77]
	s_nop 0
	v_pk_add_f32 v[68:69], v[68:69], v[70:71]
	s_nop 0
	v_add_f32_e32 v68, v68, v69
	v_fmamk_f32 v68, v68, 0x3a800000, v155
	v_rsq_f32_e32 v68, v68

; __device__ __forceinline__ unsigned cvt_pk_bf16(float lo, float hi) { f32x2 v = {lo, hi}; return __builtin_bit_cast(unsigned, __builtin_convertvector(v, nbf16x2e)); }
;     __device__ __forceinline__ void operator()(const f32x4 (&acc)[2][2][4][2], const Unit& u, int wr, int wc, int fr, int fq) const {
;     ...
;                 const int row = row0 + ai * HALF + m * 16;
;                 float rs;
;                 if (rsc) rs = rsc[row - rbase];
;                 else {
;                     const f32x4* pp = (const f32x4*)(part + (size_t)row * 16);
;                     const f32x4 p0 = pp[0], p1 = pp[1], p2 = pp[2], p3 = pp[3];
;                     const float ssq = ((p0[0] + p0[1]) + (p0[2] + p0[3])) + ((p1[0] + p1[1]) + (p1[2] + p1[3])) + ((p2[0] + p2[1]) + (p2[2] + p2[3])) + ((p3[0] + p3[1]) + (p3[2] + p3[3]));
;                     rs = __builtin_amdgcn_rsqf(ssq * (1.0f / 1024.0f) + 1e-6f);
;                 }
;                 float v[8];
; #pragma unroll
;                 for (int n = 0; n < 2; ++n)
; #pragma unroll
;                     for (int i = 0; i < 4; ++i) { const float g = acc[ai][0][m][n][i] * rs, up = acc[ai][1][m][n][i] * rs; v[4 * n + i] = g * __builtin_amdgcn_rcpf(1.0f + __expf(-g)) * up; }
;                 u32x4 w; w.x = cvt_pk_bf16(v[0], v[1]); w.y = cvt_pk_bf16(v[2], v[3]); w.z = cvt_pk_bf16(v[4], v[5]); w.w = cvt_pk_bf16(v[6], v[7]);
;                 *(u32x4*)(O + (size_t)row * 2816 + u.pn * HALF + wc * 32 + 8 * fq) = w;
.LBB0_763:
	s_waitcnt lgkmcnt(0)
	v_pk_mul_f32 v[62:63], v[62:63], v[68:69] op_sel_hi:[1,0]
	s_and_b64 vcc, exec, s[36:37]
	v_mul_f32_e32 v69, 0xbfb8aa3b, v62
	v_exp_f32_e32 v69, v69
	v_mul_f32_e32 v70, 0xbfb8aa3b, v63
	v_exp_f32_e32 v71, v70
	v_pk_mul_f32 v[54:55], v[54:55], v[68:69] op_sel_hi:[1,0]
	v_add_f32_e32 v69, 1.0, v69
	v_rcp_f32_e32 v70, v69
	v_add_f32_e32 v69, 1.0, v71
	v_pk_mul_f32 v[64:65], v[64:65], v[68:69] op_sel_hi:[1,0]
	s_nop 0
	v_mul_f32_e32 v71, 0xbfb8aa3b, v64
	v_exp_f32_e32 v72, v71
	v_mul_f32_e32 v71, 0xbfb8aa3b, v65
	v_exp_f32_e32 v73, v71
	v_rcp_f32_e32 v71, v69
	v_add_f32_e32 v69, 1.0, v72
	v_rcp_f32_e32 v72, v69
	v_add_f32_e32 v69, 1.0, v73
	v_rcp_f32_e32 v73, v69
	v_pk_mul_f32 v[62:63], v[62:63], v[70:71]
	v_pk_mul_f32 v[58:59], v[58:59], v[68:69] op_sel_hi:[1,0]
	v_pk_mul_f32 v[54:55], v[54:55], v[62:63]
	v_pk_mul_f32 v[62:63], v[64:65], v[72:73]
	v_mul_f32_e32 v64, 0xbfb8aa3b, v58
	v_exp_f32_e32 v64, v64
	v_pk_mul_f32 v[56:57], v[56:57], v[68:69] op_sel_hi:[1,0]
	v_pk_mul_f32 v[60:61], v[60:61], v[68:69] op_sel_hi:[1,0]
	v_pk_mul_f32 v[56:57], v[56:57], v[62:63]
	v_mul_f32_e32 v62, 0xbfb8aa3b, v59
	v_exp_f32_e32 v63, v62
	v_add_f32_e32 v62, 1.0, v64
	v_mul_f32_e32 v64, 0xbfb8aa3b, v60
	v_mul_f32_e32 v65, 0xbfb8aa3b, v61
	v_exp_f32_e32 v64, v64
	v_exp_f32_e32 v65, v65
	v_add_f32_e32 v63, 1.0, v63
	v_rcp_f32_e32 v62, v62
	v_rcp_f32_e32 v63, v63
	v_add_f32_e32 v64, 1.0, v64
	v_add_f32_e32 v65, 1.0, v65
	v_rcp_f32_e32 v64, v64
	v_rcp_f32_e32 v65, v65
	v_pk_mul_f32 v[50:51], v[50:51], v[68:69] op_sel_hi:[1,0]
	v_pk_mul_f32 v[58:59], v[58:59], v[62:63]
	s_nop 0
	v_pk_mul_f32 v[58:59], v[50:51], v[58:59]
	v_pk_mul_f32 v[50:51], v[52:53], v[68:69] op_sel_hi:[1,0]
	v_pk_mul_f32 v[52:53], v[60:61], v[64:65]
	s_nop 0
	v_pk_mul_f32 v[60:61], v[50:51], v[52:53]
	v_cvt_pk_bf16_f32 v50, v54, v55
	v_cvt_pk_bf16_f32 v51, v56, v57
	v_cvt_pk_bf16_f32 v52, v58, v59
	v_cvt_pk_bf16_f32 v53, v60, v61
	v_lshl_add_u64 v[236:237], v[236:237], 0, s[98:99]
	global_store_dwordx4 v[236:237], v[50:53], off
	s_mov_b64 s[26:27], -1
	s_nop 0
	v_add_u32_e32 v50, 0x90, v148
	v_ashrrev_i32_e32 v51, 31, v50
	s_cbranch_vccz .LBB0_765
	v_lshlrev_b64 v[52:53], 6, v[50:51]
	v_lshl_add_u64 v[64:65], s[8:9], 0, v[52:53]
	global_load_dwordx4 v[52:55], v[64:65], off
	global_load_dwordx4 v[56:59], v[64:65], off offset:16
	global_load_dwordx4 v[60:63], v[64:65], off offset:32
	s_nop 0
	global_load_dwordx4 v[64:67], v[64:65], off offset:48
	s_mov_b64 s[26:27], 0
	s_waitcnt vmcnt(0)
	v_mov_b32_e32 v68, v53
	v_mov_b32_e32 v69, v54
	v_mov_b32_e32 v53, v55
	v_mov_b32_e32 v54, v57
	v_mov_b32_e32 v55, v58
	v_mov_b32_e32 v57, v59
	v_pk_add_f32 v[52:53], v[68:69], v[52:53]
	v_pk_add_f32 v[54:55], v[54:55], v[56:57]
	v_pk_add_f32 v[52:53], v[52:53], v[52:53] op_sel:[0,1] op_sel_hi:[1,0]
	v_pk_add_f32 v[54:55], v[54:55], v[54:55] op_sel:[0,1] op_sel_hi:[1,0]
	v_add_f32_e32 v58, v60, v61
	v_add_f32_e32 v60, v62, v63
	v_mov_b32_e32 v59, v66
	v_mov_b32_e32 v61, v67
	v_mov_b32_e32 v53, v64
	v_mov_b32_e32 v55, v65
	v_pk_add_f32 v[52:53], v[52:53], v[54:55]
	v_pk_add_f32 v[54:55], v[58:59], v[60:61]
	s_nop 0
	v_pk_add_f32 v[52:53], v[52:53], v[54:55]
	s_nop 0
	v_add_f32_e32 v52, v52, v53
	v_fmamk_f32 v52, v52, 0x3a800000, v155
	v_rsq_f32_e32 v52, v52

; __device__ __forceinline__ unsigned cvt_pk_bf16(float lo, float hi) { f32x2 v = {lo, hi}; return __builtin_bit_cast(unsigned, __builtin_convertvector(v, nbf16x2e)); }
;     __device__ __forceinline__ void operator()(const f32x4 (&acc)[2][2][4][2], const Unit& u, int wr, int wc, int fr, int fq) const {
;     ...
;                 const int row = row0 + ai * HALF + m * 16;
;                 float rs;
;                 if (rsc) rs = rsc[row - rbase];
;                 else {
;                     const f32x4* pp = (const f32x4*)(part + (size_t)row * 16);
;                     const f32x4 p0 = pp[0], p1 = pp[1], p2 = pp[2], p3 = pp[3];
;                     const float ssq = ((p0[0] + p0[1]) + (p0[2] + p0[3])) + ((p1[0] + p1[1]) + (p1[2] + p1[3])) + ((p2[0] + p2[1]) + (p2[2] + p2[3])) + ((p3[0] + p3[1]) + (p3[2] + p3[3]));
;                     rs = __builtin_amdgcn_rsqf(ssq * (1.0f / 1024.0f) + 1e-6f);
;                 }
;                 float v[8];
; #pragma unroll
;                 for (int n = 0; n < 2; ++n)
; #pragma unroll
;                     for (int i = 0; i < 4; ++i) { const float g = acc[ai][0][m][n][i] * rs, up = acc[ai][1][m][n][i] * rs; v[4 * n + i] = g * __builtin_amdgcn_rcpf(1.0f + __expf(-g)) * up; }
;                 u32x4 w; w.x = cvt_pk_bf16(v[0], v[1]); w.y = cvt_pk_bf16(v[2], v[3]); w.z = cvt_pk_bf16(v[4], v[5]); w.w = cvt_pk_bf16(v[6], v[7]);
;                 *(u32x4*)(O + (size_t)row * 2816 + u.pn * HALF + wc * 32 + 8 * fq) = w;
.LBB0_767:
	s_waitcnt lgkmcnt(0)
	v_pk_mul_f32 v[46:47], v[46:47], v[52:53] op_sel_hi:[1,0]
	s_and_b64 vcc, exec, s[36:37]
	v_mul_f32_e32 v53, 0xbfb8aa3b, v46
	v_exp_f32_e32 v53, v53
	v_mul_f32_e32 v54, 0xbfb8aa3b, v47
	v_exp_f32_e32 v55, v54
	v_pk_mul_f32 v[38:39], v[38:39], v[52:53] op_sel_hi:[1,0]
	v_add_f32_e32 v53, 1.0, v53
	v_rcp_f32_e32 v54, v53
	v_add_f32_e32 v53, 1.0, v55
	v_pk_mul_f32 v[48:49], v[48:49], v[52:53] op_sel_hi:[1,0]
	s_nop 0
	v_mul_f32_e32 v55, 0xbfb8aa3b, v48
	v_exp_f32_e32 v56, v55
	v_mul_f32_e32 v55, 0xbfb8aa3b, v49
	v_exp_f32_e32 v57, v55
	v_rcp_f32_e32 v55, v53
	v_add_f32_e32 v53, 1.0, v56
	v_rcp_f32_e32 v56, v53
	v_add_f32_e32 v53, 1.0, v57
	v_rcp_f32_e32 v57, v53
	v_pk_mul_f32 v[46:47], v[46:47], v[54:55]
	v_pk_mul_f32 v[42:43], v[42:43], v[52:53] op_sel_hi:[1,0]
	v_pk_mul_f32 v[38:39], v[38:39], v[46:47]
	v_pk_mul_f32 v[46:47], v[48:49], v[56:57]
	v_mul_f32_e32 v48, 0xbfb8aa3b, v42
	v_exp_f32_e32 v48, v48
	v_pk_mul_f32 v[40:41], v[40:41], v[52:53] op_sel_hi:[1,0]
	v_pk_mul_f32 v[44:45], v[44:45], v[52:53] op_sel_hi:[1,0]
	v_pk_mul_f32 v[40:41], v[40:41], v[46:47]
	v_mul_f32_e32 v46, 0xbfb8aa3b, v43
	v_exp_f32_e32 v47, v46
	v_add_f32_e32 v46, 1.0, v48
	v_mul_f32_e32 v48, 0xbfb8aa3b, v44
	v_mul_f32_e32 v49, 0xbfb8aa3b, v45
	v_exp_f32_e32 v48, v48
	v_exp_f32_e32 v49, v49
	v_add_f32_e32 v47, 1.0, v47
	v_rcp_f32_e32 v46, v46
	v_rcp_f32_e32 v47, v47
	v_add_f32_e32 v48, 1.0, v48
	v_add_f32_e32 v49, 1.0, v49
	v_rcp_f32_e32 v48, v48
	v_rcp_f32_e32 v49, v49
	v_pk_mul_f32 v[34:35], v[34:35], v[52:53] op_sel_hi:[1,0]
	v_pk_mul_f32 v[42:43], v[42:43], v[46:47]
	s_nop 0
	v_pk_mul_f32 v[42:43], v[34:35], v[42:43]
	v_pk_mul_f32 v[34:35], v[36:37], v[52:53] op_sel_hi:[1,0]
	v_pk_mul_f32 v[36:37], v[44:45], v[48:49]
	s_nop 0
	v_pk_mul_f32 v[44:45], v[34:35], v[36:37]
	v_cvt_pk_bf16_f32 v34, v38, v39
	v_cvt_pk_bf16_f32 v35, v40, v41
	v_cvt_pk_bf16_f32 v36, v42, v43
	v_cvt_pk_bf16_f32 v37, v44, v45
	v_lshl_add_u64 v[236:237], v[236:237], 0, s[100:101]
	global_store_dwordx4 v[236:237], v[34:37], off
	s_mov_b64 s[26:27], -1
	s_nop 0
	v_add_u32_e32 v34, 0xa0, v148
	v_ashrrev_i32_e32 v35, 31, v34
	s_cbranch_vccz .LBB0_769
	v_lshlrev_b64 v[36:37], 6, v[34:35]
	v_lshl_add_u64 v[48:49], s[8:9], 0, v[36:37]
	global_load_dwordx4 v[36:39], v[48:49], off
	global_load_dwordx4 v[40:43], v[48:49], off offset:16
	global_load_dwordx4 v[44:47], v[48:49], off offset:32
	s_nop 0
	global_load_dwordx4 v[48:51], v[48:49], off offset:48
	s_mov_b64 s[26:27], 0
	s_waitcnt vmcnt(0)
	v_mov_b32_e32 v52, v37
	v_mov_b32_e32 v53, v38
	v_mov_b32_e32 v37, v39
	v_mov_b32_e32 v38, v41
	v_mov_b32_e32 v39, v42
	v_mov_b32_e32 v41, v43
	v_pk_add_f32 v[36:37], v[52:53], v[36:37]
	v_pk_add_f32 v[38:39], v[38:39], v[40:41]
	v_pk_add_f32 v[36:37], v[36:37], v[36:37] op_sel:[0,1] op_sel_hi:[1,0]
	v_pk_add_f32 v[38:39], v[38:39], v[38:39] op_sel:[0,1] op_sel_hi:[1,0]
	v_add_f32_e32 v42, v44, v45
	v_add_f32_e32 v44, v46, v47
	v_mov_b32_e32 v43, v50
	v_mov_b32_e32 v45, v51
	v_mov_b32_e32 v37, v48
	v_mov_b32_e32 v39, v49
	v_pk_add_f32 v[36:37], v[36:37], v[38:39]
	v_pk_add_f32 v[38:39], v[42:43], v[44:45]
	s_nop 0
	v_pk_add_f32 v[36:37], v[36:37], v[38:39]
	s_nop 0
	v_add_f32_e32 v36, v36, v37
	v_fmamk_f32 v36, v36, 0x3a800000, v155
	v_rsq_f32_e32 v36, v36

; __device__ __forceinline__ unsigned cvt_pk_bf16(float lo, float hi) { f32x2 v = {lo, hi}; return __builtin_bit_cast(unsigned, __builtin_convertvector(v, nbf16x2e)); }
;     __device__ __forceinline__ void operator()(const f32x4 (&acc)[2][2][4][2], const Unit& u, int wr, int wc, int fr, int fq) const {
;     ...
;                 const int row = row0 + ai * HALF + m * 16;
;                 float rs;
;                 if (rsc) rs = rsc[row - rbase];
;                 else {
;                     const f32x4* pp = (const f32x4*)(part + (size_t)row * 16);
;                     const f32x4 p0 = pp[0], p1 = pp[1], p2 = pp[2], p3 = pp[3];
;                     const float ssq = ((p0[0] + p0[1]) + (p0[2] + p0[3])) + ((p1[0] + p1[1]) + (p1[2] + p1[3])) + ((p2[0] + p2[1]) + (p2[2] + p2[3])) + ((p3[0] + p3[1]) + (p3[2] + p3[3]));
;                     rs = __builtin_amdgcn_rsqf(ssq * (1.0f / 1024.0f) + 1e-6f);
;                 }
;                 float v[8];
; #pragma unroll
;                 for (int n = 0; n < 2; ++n)
; #pragma unroll
;                     for (int i = 0; i < 4; ++i) { const float g = acc[ai][0][m][n][i] * rs, up = acc[ai][1][m][n][i] * rs; v[4 * n + i] = g * __builtin_amdgcn_rcpf(1.0f + __expf(-g)) * up; }
;                 u32x4 w; w.x = cvt_pk_bf16(v[0], v[1]); w.y = cvt_pk_bf16(v[2], v[3]); w.z = cvt_pk_bf16(v[4], v[5]); w.w = cvt_pk_bf16(v[6], v[7]);
;                 *(u32x4*)(O + (size_t)row * 2816 + u.pn * HALF + wc * 32 + 8 * fq) = w;
.LBB0_771:
	s_waitcnt lgkmcnt(0)
	v_pk_mul_f32 v[30:31], v[30:31], v[36:37] op_sel_hi:[1,0]
	s_and_b64 vcc, exec, s[36:37]
	v_mul_f32_e32 v37, 0xbfb8aa3b, v30
	v_exp_f32_e32 v37, v37
	v_mul_f32_e32 v38, 0xbfb8aa3b, v31
	v_exp_f32_e32 v39, v38
	v_pk_mul_f32 v[22:23], v[22:23], v[36:37] op_sel_hi:[1,0]
	v_add_f32_e32 v37, 1.0, v37
	v_rcp_f32_e32 v38, v37
	v_add_f32_e32 v37, 1.0, v39
	v_pk_mul_f32 v[32:33], v[32:33], v[36:37] op_sel_hi:[1,0]
	s_nop 0
	v_mul_f32_e32 v39, 0xbfb8aa3b, v32
	v_exp_f32_e32 v40, v39
	v_mul_f32_e32 v39, 0xbfb8aa3b, v33
	v_exp_f32_e32 v41, v39
	v_rcp_f32_e32 v39, v37
	v_add_f32_e32 v37, 1.0, v40
	v_rcp_f32_e32 v40, v37
	v_add_f32_e32 v37, 1.0, v41
	v_rcp_f32_e32 v41, v37
	v_pk_mul_f32 v[30:31], v[30:31], v[38:39]
	v_pk_mul_f32 v[26:27], v[26:27], v[36:37] op_sel_hi:[1,0]
	v_pk_mul_f32 v[22:23], v[22:23], v[30:31]
	v_pk_mul_f32 v[30:31], v[32:33], v[40:41]
	v_mul_f32_e32 v32, 0xbfb8aa3b, v26
	v_exp_f32_e32 v32, v32
	v_pk_mul_f32 v[24:25], v[24:25], v[36:37] op_sel_hi:[1,0]
	v_pk_mul_f32 v[28:29], v[28:29], v[36:37] op_sel_hi:[1,0]
	v_pk_mul_f32 v[24:25], v[24:25], v[30:31]
	v_mul_f32_e32 v30, 0xbfb8aa3b, v27
	v_exp_f32_e32 v31, v30
	v_add_f32_e32 v30, 1.0, v32
	v_mul_f32_e32 v32, 0xbfb8aa3b, v28
	v_mul_f32_e32 v33, 0xbfb8aa3b, v29
	v_exp_f32_e32 v32, v32
	v_exp_f32_e32 v33, v33
	v_add_f32_e32 v31, 1.0, v31
	v_rcp_f32_e32 v30, v30
	v_rcp_f32_e32 v31, v31
	v_add_f32_e32 v32, 1.0, v32
	v_add_f32_e32 v33, 1.0, v33
	v_rcp_f32_e32 v32, v32
	v_rcp_f32_e32 v33, v33
	v_pk_mul_f32 v[18:19], v[18:19], v[36:37] op_sel_hi:[1,0]
	v_pk_mul_f32 v[26:27], v[26:27], v[30:31]
	s_nop 0
	v_pk_mul_f32 v[26:27], v[18:19], v[26:27]
	v_pk_mul_f32 v[18:19], v[20:21], v[36:37] op_sel_hi:[1,0]
	v_pk_mul_f32 v[20:21], v[28:29], v[32:33]
	s_nop 0
	v_pk_mul_f32 v[28:29], v[18:19], v[20:21]
	v_cvt_pk_bf16_f32 v18, v22, v23
	v_cvt_pk_bf16_f32 v19, v24, v25
	v_cvt_pk_bf16_f32 v20, v26, v27
	v_cvt_pk_bf16_f32 v21, v28, v29
	v_lshl_add_u64 v[236:237], v[236:237], 0, s[100:101]
	global_store_dwordx4 v[236:237], v[18:21], off
	s_mov_b64 s[26:27], -1
	s_nop 0
	v_add_u32_e32 v18, 0xb0, v148
	v_ashrrev_i32_e32 v19, 31, v18
	s_cbranch_vccz .LBB0_773
	v_lshlrev_b64 v[20:21], 6, v[18:19]
	v_lshl_add_u64 v[32:33], s[8:9], 0, v[20:21]
	global_load_dwordx4 v[20:23], v[32:33], off
	global_load_dwordx4 v[24:27], v[32:33], off offset:16
	global_load_dwordx4 v[28:31], v[32:33], off offset:32
	s_nop 0
	global_load_dwordx4 v[32:35], v[32:33], off offset:48
	s_mov_b64 s[26:27], 0
	s_waitcnt vmcnt(0)
	v_mov_b32_e32 v36, v21
	v_mov_b32_e32 v37, v22
	v_mov_b32_e32 v21, v23
	v_mov_b32_e32 v22, v25
	v_mov_b32_e32 v23, v26
	v_mov_b32_e32 v25, v27
	v_pk_add_f32 v[20:21], v[36:37], v[20:21]
	v_pk_add_f32 v[22:23], v[22:23], v[24:25]
	v_pk_add_f32 v[20:21], v[20:21], v[20:21] op_sel:[0,1] op_sel_hi:[1,0]
	v_pk_add_f32 v[22:23], v[22:23], v[22:23] op_sel:[0,1] op_sel_hi:[1,0]
	v_add_f32_e32 v26, v28, v29
	v_add_f32_e32 v28, v30, v31
	v_mov_b32_e32 v27, v34
	v_mov_b32_e32 v29, v35
	v_mov_b32_e32 v21, v32
	v_mov_b32_e32 v23, v33
	v_pk_add_f32 v[20:21], v[20:21], v[22:23]
	v_pk_add_f32 v[22:23], v[26:27], v[28:29]
	s_nop 0
	v_pk_add_f32 v[20:21], v[20:21], v[22:23]
	s_nop 0
	v_add_f32_e32 v20, v20, v21
	v_fmamk_f32 v20, v20, 0x3a800000, v155
	v_rsq_f32_e32 v20, v20

; __device__ __forceinline__ unsigned cvt_pk_bf16(float lo, float hi) { f32x2 v = {lo, hi}; return __builtin_bit_cast(unsigned, __builtin_convertvector(v, nbf16x2e)); }
;     __device__ __forceinline__ void operator()(const f32x4 (&acc)[2][2][4][2], const Unit& u, int wr, int wc, int fr, int fq) const {
;     ...
;                 const int row = row0 + ai * HALF + m * 16;
;                 float rs;
;                 if (rsc) rs = rsc[row - rbase];
;                 else {
;                     const f32x4* pp = (const f32x4*)(part + (size_t)row * 16);
;                     const f32x4 p0 = pp[0], p1 = pp[1], p2 = pp[2], p3 = pp[3];
;                     const float ssq = ((p0[0] + p0[1]) + (p0[2] + p0[3])) + ((p1[0] + p1[1]) + (p1[2] + p1[3])) + ((p2[0] + p2[1]) + (p2[2] + p2[3])) + ((p3[0] + p3[1]) + (p3[2] + p3[3]));
;                     rs = __builtin_amdgcn_rsqf(ssq * (1.0f / 1024.0f) + 1e-6f);
;                 }
;                 float v[8];
; #pragma unroll
;                 for (int n = 0; n < 2; ++n)
; #pragma unroll
;                     for (int i = 0; i < 4; ++i) { const float g = acc[ai][0][m][n][i] * rs, up = acc[ai][1][m][n][i] * rs; v[4 * n + i] = g * __builtin_amdgcn_rcpf(1.0f + __expf(-g)) * up; }
;                 u32x4 w; w.x = cvt_pk_bf16(v[0], v[1]); w.y = cvt_pk_bf16(v[2], v[3]); w.z = cvt_pk_bf16(v[4], v[5]); w.w = cvt_pk_bf16(v[6], v[7]);
;                 *(u32x4*)(O + (size_t)row * 2816 + u.pn * HALF + wc * 32 + 8 * fq) = w;
.LBB0_775:
	s_waitcnt lgkmcnt(0)
	v_pk_mul_f32 v[14:15], v[14:15], v[20:21] op_sel_hi:[1,0]
	s_andn2_b64 vcc, exec, s[0:1]
	v_mul_f32_e32 v21, 0xbfb8aa3b, v14
	v_exp_f32_e32 v21, v21
	v_mul_f32_e32 v22, 0xbfb8aa3b, v15
	v_exp_f32_e32 v23, v22
	s_mov_b64 s[0:1], -1
	v_pk_mul_f32 v[6:7], v[6:7], v[20:21] op_sel_hi:[1,0]
	v_add_f32_e32 v21, 1.0, v21
	v_rcp_f32_e32 v22, v21
	v_add_f32_e32 v21, 1.0, v23
	v_pk_mul_f32 v[16:17], v[16:17], v[20:21] op_sel_hi:[1,0]
	s_nop 0
	v_mul_f32_e32 v23, 0xbfb8aa3b, v16
	v_exp_f32_e32 v24, v23
	v_mul_f32_e32 v23, 0xbfb8aa3b, v17
	v_exp_f32_e32 v25, v23
	v_rcp_f32_e32 v23, v21
	v_add_f32_e32 v21, 1.0, v24
	v_rcp_f32_e32 v24, v21
	v_add_f32_e32 v21, 1.0, v25
	v_rcp_f32_e32 v25, v21
	v_pk_mul_f32 v[14:15], v[14:15], v[22:23]
	v_pk_mul_f32 v[10:11], v[10:11], v[20:21] op_sel_hi:[1,0]
	v_pk_mul_f32 v[6:7], v[6:7], v[14:15]
	v_pk_mul_f32 v[14:15], v[16:17], v[24:25]
	v_mul_f32_e32 v16, 0xbfb8aa3b, v10
	v_exp_f32_e32 v16, v16
	v_pk_mul_f32 v[8:9], v[8:9], v[20:21] op_sel_hi:[1,0]
	v_pk_mul_f32 v[12:13], v[12:13], v[20:21] op_sel_hi:[1,0]
	v_pk_mul_f32 v[8:9], v[8:9], v[14:15]
	v_mul_f32_e32 v14, 0xbfb8aa3b, v11
	v_exp_f32_e32 v15, v14
	v_add_f32_e32 v14, 1.0, v16
	v_mul_f32_e32 v16, 0xbfb8aa3b, v12
	v_mul_f32_e32 v17, 0xbfb8aa3b, v13
	v_exp_f32_e32 v16, v16
	v_exp_f32_e32 v17, v17
	v_add_f32_e32 v15, 1.0, v15
	v_rcp_f32_e32 v14, v14
	v_rcp_f32_e32 v15, v15
	v_add_f32_e32 v16, 1.0, v16
	v_add_f32_e32 v17, 1.0, v17
	v_rcp_f32_e32 v16, v16
	v_rcp_f32_e32 v17, v17
	v_pk_mul_f32 v[2:3], v[2:3], v[20:21] op_sel_hi:[1,0]
	v_pk_mul_f32 v[10:11], v[10:11], v[14:15]
	s_nop 0
	v_pk_mul_f32 v[10:11], v[2:3], v[10:11]
	v_pk_mul_f32 v[2:3], v[4:5], v[20:21] op_sel_hi:[1,0]
	v_pk_mul_f32 v[4:5], v[12:13], v[16:17]
	s_nop 0
	v_pk_mul_f32 v[12:13], v[2:3], v[4:5]
	v_cvt_pk_bf16_f32 v2, v6, v7
	v_cvt_pk_bf16_f32 v3, v8, v9
	v_cvt_pk_bf16_f32 v4, v10, v11
	v_cvt_pk_bf16_f32 v5, v12, v13
	v_lshl_add_u64 v[236:237], v[236:237], 0, s[100:101]
	global_store_dwordx4 v[236:237], v[2:5], off
	s_cbranch_vccnz .LBB0_736
	s_andn2_b64 vcc, exec, s[10:11]
	s_cbranch_vccnz .LBB0_735
	s_barrier
	s_branch .LBB0_735
